# instruction selection: accumulator zeroing with 63 v_mov_b64 instead of 127 v_mov_b32 per unit (all six GEMM instances)
# speedup vs baseline: 1.0058x; 1.0058x over previous
; template <class Epi>
; __device__ __forceinline__ void gemm_phase(LAS unsigned char* lds, const Gemm g, const Sched& S, const Epi& E) {
;     ...
;         const bool has_next = S.next(ui + 1, nxt);
;         const char* nA = has_next ? (const char*)g.A + nxt.ao : cA; const char* nB = has_next ? (const char*)g.Bt + nxt.bo : cB;
;     ...
; #pragma unroll
;         for (int a = 0; a < 2; ++a)
; #pragma unroll
;             for (int b = 0; b < 2; ++b)
; #pragma unroll
;                 for (int m = 0; m < 4; ++m)
; #pragma unroll
;                     for (int n = 0; n < 2; ++n) acc[a][b][m][n] = (f32x4){0.f, 0.f, 0.f, 0.f};
;         cur = nxt; cA = nA; cB = nB; ++ui;
.LBB0_399:
	v_mov_b64_e32 v[2:3], s[26:27]
	v_readlane_b32 s8, v254, 11
	v_cmp_lt_i64_e32 vcc, s[88:89], v[2:3]
	v_readlane_b32 s9, v254, 12
	s_add_u32 s88, s8, s84
	s_addc_u32 s89, s9, s85
	s_and_b64 s[14:15], vcc, exec
	s_cselect_b32 s55, s89, s93
	s_cselect_b32 s57, s88, s92
	s_add_u32 s90, s10, s86
	s_addc_u32 s91, s11, s87
	s_and_b64 s[14:15], vcc, exec
	s_cselect_b32 s59, s91, s95
	s_cselect_b32 s65, s90, s94
	s_add_u32 s92, s92, 0x80
	s_addc_u32 s93, s93, 0
	s_add_u32 s34, s94, 0x100
	v_mov_b32_e32 v2, 0
	s_addc_u32 s35, s95, 0
	s_mov_b32 s66, 0
	s_waitcnt lgkmcnt(0)
	v_mov_b32_e32 v3, v2
	v_mov_b64_e32 v[4:5], v[2:3]
	v_mov_b64_e32 v[6:7], v[2:3]
	v_mov_b64_e32 v[8:9], v[2:3]
	v_mov_b64_e32 v[10:11], v[2:3]
	v_mov_b64_e32 v[12:13], v[2:3]
	v_mov_b64_e32 v[14:15], v[2:3]
	v_mov_b64_e32 v[16:17], v[2:3]
	v_mov_b64_e32 v[18:19], v[2:3]
	v_mov_b64_e32 v[20:21], v[2:3]
	v_mov_b64_e32 v[22:23], v[2:3]
	v_mov_b64_e32 v[24:25], v[2:3]
	v_mov_b64_e32 v[26:27], v[2:3]
	v_mov_b64_e32 v[28:29], v[2:3]
	v_mov_b64_e32 v[30:31], v[2:3]
	v_mov_b64_e32 v[32:33], v[2:3]
	v_mov_b64_e32 v[34:35], v[2:3]
	v_mov_b64_e32 v[36:37], v[2:3]
	v_mov_b64_e32 v[38:39], v[2:3]
	v_mov_b64_e32 v[40:41], v[2:3]
	v_mov_b64_e32 v[42:43], v[2:3]
	v_mov_b64_e32 v[44:45], v[2:3]
	v_mov_b64_e32 v[46:47], v[2:3]
	v_mov_b64_e32 v[48:49], v[2:3]
	v_mov_b64_e32 v[50:51], v[2:3]
	v_mov_b64_e32 v[52:53], v[2:3]
	v_mov_b64_e32 v[54:55], v[2:3]
	v_mov_b64_e32 v[56:57], v[2:3]
	v_mov_b64_e32 v[58:59], v[2:3]
	v_mov_b64_e32 v[60:61], v[2:3]
	v_mov_b64_e32 v[62:63], v[2:3]
	v_mov_b64_e32 v[64:65], v[2:3]
	v_mov_b64_e32 v[66:67], v[2:3]
	v_mov_b64_e32 v[68:69], v[2:3]
	v_mov_b64_e32 v[70:71], v[2:3]
	v_mov_b64_e32 v[72:73], v[2:3]
	v_mov_b64_e32 v[74:75], v[2:3]
	v_mov_b64_e32 v[76:77], v[2:3]
	v_mov_b64_e32 v[78:79], v[2:3]
	v_mov_b64_e32 v[80:81], v[2:3]
	v_mov_b64_e32 v[82:83], v[2:3]
	v_mov_b64_e32 v[84:85], v[2:3]
	v_mov_b64_e32 v[86:87], v[2:3]
	v_mov_b64_e32 v[88:89], v[2:3]
	v_mov_b64_e32 v[90:91], v[2:3]
	v_mov_b64_e32 v[92:93], v[2:3]
	v_mov_b64_e32 v[94:95], v[2:3]
	v_mov_b64_e32 v[96:97], v[2:3]
	v_mov_b64_e32 v[98:99], v[2:3]
	v_mov_b64_e32 v[100:101], v[2:3]
	v_mov_b64_e32 v[102:103], v[2:3]
	v_mov_b64_e32 v[104:105], v[2:3]
	v_mov_b64_e32 v[106:107], v[2:3]
	v_mov_b64_e32 v[108:109], v[2:3]
	v_mov_b64_e32 v[110:111], v[2:3]
	v_mov_b64_e32 v[112:113], v[2:3]
	v_mov_b64_e32 v[114:115], v[2:3]
	v_mov_b64_e32 v[116:117], v[2:3]
	v_mov_b64_e32 v[118:119], v[2:3]
	v_mov_b64_e32 v[120:121], v[2:3]
	v_mov_b64_e32 v[122:123], v[2:3]
	v_mov_b64_e32 v[124:125], v[2:3]
	v_mov_b64_e32 v[126:127], v[2:3]
	v_mov_b64_e32 v[128:129], v[2:3]
	v_readfirstlane_b32 s98, v219
	s_nop 1
	s_bitcmp1_b32 s98, 8
	s_cbranch_scc0 .Lresync_y_400
	s_barrier

; template <class Epi>
; __device__ __forceinline__ void gemm_phase(LAS unsigned char* lds, const Gemm g, const Sched& S, const Epi& E) {
;     ...
;         const bool has_next = S.next(ui + 1, nxt);
;         const char* nA = has_next ? (const char*)g.A + nxt.ao : cA; const char* nB = has_next ? (const char*)g.Bt + nxt.bo : cB;
;     ...
; #pragma unroll
;         for (int a = 0; a < 2; ++a)
; #pragma unroll
;             for (int b = 0; b < 2; ++b)
; #pragma unroll
;                 for (int m = 0; m < 4; ++m)
; #pragma unroll
;                     for (int n = 0; n < 2; ++n) acc[a][b][m][n] = (f32x4){0.f, 0.f, 0.f, 0.f};
;         cur = nxt; cA = nA; cB = nB; ++ui;
.LBB0_460:
	v_mov_b64_e32 v[2:3], s[26:27]
	v_readlane_b32 s8, v254, 11
	v_cmp_lt_i64_e32 vcc, s[84:85], v[2:3]
	v_readlane_b32 s9, v254, 12
	s_add_u32 s84, s8, s80
	s_addc_u32 s85, s9, s81
	s_and_b64 s[14:15], vcc, exec
	s_cselect_b32 s71, s85, s5
	s_cselect_b32 s57, s84, s4
	s_add_u32 s86, s10, s82
	s_addc_u32 s87, s11, s83
	s_and_b64 s[14:15], vcc, exec
	s_cselect_b32 s59, s87, s89
	s_cselect_b32 s72, s86, s88
	s_add_u32 s4, s4, 0x80
	s_addc_u32 s5, s5, 0
	s_add_u32 s34, s88, 0x100
	v_mov_b32_e32 v2, 0
	s_addc_u32 s35, s89, 0
	s_mov_b32 s88, 0
	s_waitcnt lgkmcnt(0)
	v_mov_b32_e32 v3, v2
	v_mov_b64_e32 v[4:5], v[2:3]
	v_mov_b64_e32 v[6:7], v[2:3]
	v_mov_b64_e32 v[8:9], v[2:3]
	v_mov_b64_e32 v[10:11], v[2:3]
	v_mov_b64_e32 v[12:13], v[2:3]
	v_mov_b64_e32 v[14:15], v[2:3]
	v_mov_b64_e32 v[16:17], v[2:3]
	v_mov_b64_e32 v[18:19], v[2:3]
	v_mov_b64_e32 v[20:21], v[2:3]
	v_mov_b64_e32 v[22:23], v[2:3]
	v_mov_b64_e32 v[24:25], v[2:3]
	v_mov_b64_e32 v[26:27], v[2:3]
	v_mov_b64_e32 v[28:29], v[2:3]
	v_mov_b64_e32 v[30:31], v[2:3]
	v_mov_b64_e32 v[32:33], v[2:3]
	v_mov_b64_e32 v[34:35], v[2:3]
	v_mov_b64_e32 v[36:37], v[2:3]
	v_mov_b64_e32 v[38:39], v[2:3]
	v_mov_b64_e32 v[40:41], v[2:3]
	v_mov_b64_e32 v[42:43], v[2:3]
	v_mov_b64_e32 v[44:45], v[2:3]
	v_mov_b64_e32 v[46:47], v[2:3]
	v_mov_b64_e32 v[48:49], v[2:3]
	v_mov_b64_e32 v[50:51], v[2:3]
	v_mov_b64_e32 v[52:53], v[2:3]
	v_mov_b64_e32 v[54:55], v[2:3]
	v_mov_b64_e32 v[56:57], v[2:3]
	v_mov_b64_e32 v[58:59], v[2:3]
	v_mov_b64_e32 v[60:61], v[2:3]
	v_mov_b64_e32 v[62:63], v[2:3]
	v_mov_b64_e32 v[64:65], v[2:3]
	v_mov_b64_e32 v[66:67], v[2:3]
	v_mov_b64_e32 v[68:69], v[2:3]
	v_mov_b64_e32 v[70:71], v[2:3]
	v_mov_b64_e32 v[72:73], v[2:3]
	v_mov_b64_e32 v[74:75], v[2:3]
	v_mov_b64_e32 v[76:77], v[2:3]
	v_mov_b64_e32 v[78:79], v[2:3]
	v_mov_b64_e32 v[80:81], v[2:3]
	v_mov_b64_e32 v[86:87], v[2:3]
	v_mov_b64_e32 v[88:89], v[2:3]
	v_mov_b64_e32 v[90:91], v[2:3]
	v_mov_b64_e32 v[92:93], v[2:3]
	v_mov_b64_e32 v[102:103], v[2:3]
	v_mov_b64_e32 v[104:105], v[2:3]
	v_mov_b64_e32 v[106:107], v[2:3]
	v_mov_b64_e32 v[108:109], v[2:3]
	v_mov_b64_e32 v[110:111], v[2:3]
	v_mov_b64_e32 v[112:113], v[2:3]
	v_mov_b64_e32 v[118:119], v[2:3]
	v_mov_b64_e32 v[120:121], v[2:3]
	v_mov_b64_e32 v[126:127], v[2:3]
	v_mov_b64_e32 v[128:129], v[2:3]
	v_mov_b64_e32 v[134:135], v[2:3]
	v_mov_b64_e32 v[136:137], v[2:3]
	v_mov_b64_e32 v[138:139], v[2:3]
	v_mov_b64_e32 v[140:141], v[2:3]
	v_mov_b64_e32 v[142:143], v[2:3]
	v_mov_b64_e32 v[144:145], v[2:3]
	v_mov_b64_e32 v[154:155], v[2:3]
	v_mov_b64_e32 v[156:157], v[2:3]
	v_mov_b64_e32 v[158:159], v[2:3]
	v_mov_b64_e32 v[160:161], v[2:3]
	v_readfirstlane_b32 s98, v219
	s_nop 1
	s_bitcmp1_b32 s98, 8
	s_cbranch_scc0 .Lresync_y_461
	s_barrier

; template <class Epi>
; __device__ __forceinline__ void gemm_phase(LAS unsigned char* lds, const Gemm g, const Sched& S, const Epi& E) {
;     ...
;         const bool has_next = S.next(ui + 1, nxt);
;         const char* nA = has_next ? (const char*)g.A + nxt.ao : cA; const char* nB = has_next ? (const char*)g.Bt + nxt.bo : cB;
;     ...
; #pragma unroll
;         for (int a = 0; a < 2; ++a)
; #pragma unroll
;             for (int b = 0; b < 2; ++b)
; #pragma unroll
;                 for (int m = 0; m < 4; ++m)
; #pragma unroll
;                     for (int n = 0; n < 2; ++n) acc[a][b][m][n] = (f32x4){0.f, 0.f, 0.f, 0.f};
;         cur = nxt; cA = nA; cB = nB; ++ui;
.LBB0_554:
	v_mov_b64_e32 v[2:3], s[26:27]
	v_readlane_b32 s8, v254, 11
	v_cmp_lt_i64_e32 vcc, s[86:87], v[2:3]
	v_readlane_b32 s9, v254, 12
	s_add_u32 s86, s8, s82
	s_addc_u32 s87, s9, s83
	s_and_b64 s[14:15], vcc, exec
	s_cselect_b32 s55, s87, s5
	s_cselect_b32 s57, s86, s4
	s_add_u32 s88, s10, s84
	s_addc_u32 s89, s11, s85
	s_and_b64 s[14:15], vcc, exec
	s_cselect_b32 s59, s89, s7
	s_cselect_b32 s95, s88, s6
	s_add_u32 s4, s4, 0x80
	s_addc_u32 s5, s5, 0
	s_add_u32 s34, s6, 0x100
	v_mov_b32_e32 v2, 0
	s_addc_u32 s35, s7, 0
	s_mov_b32 s6, 0
	s_waitcnt lgkmcnt(0)
	v_mov_b32_e32 v3, v2
	v_mov_b64_e32 v[4:5], v[2:3]
	v_mov_b64_e32 v[6:7], v[2:3]
	v_mov_b64_e32 v[8:9], v[2:3]
	v_mov_b64_e32 v[10:11], v[2:3]
	v_mov_b64_e32 v[12:13], v[2:3]
	v_mov_b64_e32 v[14:15], v[2:3]
	v_mov_b64_e32 v[16:17], v[2:3]
	v_mov_b64_e32 v[18:19], v[2:3]
	v_mov_b64_e32 v[20:21], v[2:3]
	v_mov_b64_e32 v[22:23], v[2:3]
	v_mov_b64_e32 v[24:25], v[2:3]
	v_mov_b64_e32 v[26:27], v[2:3]
	v_mov_b64_e32 v[28:29], v[2:3]
	v_mov_b64_e32 v[30:31], v[2:3]
	v_mov_b64_e32 v[32:33], v[2:3]
	v_mov_b64_e32 v[34:35], v[2:3]
	v_mov_b64_e32 v[36:37], v[2:3]
	v_mov_b64_e32 v[38:39], v[2:3]
	v_mov_b64_e32 v[40:41], v[2:3]
	v_mov_b64_e32 v[42:43], v[2:3]
	v_mov_b64_e32 v[44:45], v[2:3]
	v_mov_b64_e32 v[46:47], v[2:3]
	v_mov_b64_e32 v[48:49], v[2:3]
	v_mov_b64_e32 v[50:51], v[2:3]
	v_mov_b64_e32 v[52:53], v[2:3]
	v_mov_b64_e32 v[54:55], v[2:3]
	v_mov_b64_e32 v[56:57], v[2:3]
	v_mov_b64_e32 v[58:59], v[2:3]
	v_mov_b64_e32 v[60:61], v[2:3]
	v_mov_b64_e32 v[62:63], v[2:3]
	v_mov_b64_e32 v[64:65], v[2:3]
	v_mov_b64_e32 v[66:67], v[2:3]
	v_mov_b64_e32 v[68:69], v[2:3]
	v_mov_b64_e32 v[70:71], v[2:3]
	v_mov_b64_e32 v[72:73], v[2:3]
	v_mov_b64_e32 v[74:75], v[2:3]
	v_mov_b64_e32 v[76:77], v[2:3]
	v_mov_b64_e32 v[78:79], v[2:3]
	v_mov_b64_e32 v[80:81], v[2:3]
	v_mov_b64_e32 v[82:83], v[2:3]
	v_mov_b64_e32 v[84:85], v[2:3]
	v_mov_b64_e32 v[86:87], v[2:3]
	v_mov_b64_e32 v[88:89], v[2:3]
	v_mov_b64_e32 v[90:91], v[2:3]
	v_mov_b64_e32 v[92:93], v[2:3]
	v_mov_b64_e32 v[94:95], v[2:3]
	v_mov_b64_e32 v[96:97], v[2:3]
	v_mov_b64_e32 v[98:99], v[2:3]
	v_mov_b64_e32 v[100:101], v[2:3]
	v_mov_b64_e32 v[102:103], v[2:3]
	v_mov_b64_e32 v[104:105], v[2:3]
	v_mov_b64_e32 v[106:107], v[2:3]
	v_mov_b64_e32 v[108:109], v[2:3]
	v_mov_b64_e32 v[110:111], v[2:3]
	v_mov_b64_e32 v[112:113], v[2:3]
	v_mov_b64_e32 v[114:115], v[2:3]
	v_mov_b64_e32 v[116:117], v[2:3]
	v_mov_b64_e32 v[118:119], v[2:3]
	v_mov_b64_e32 v[120:121], v[2:3]
	v_mov_b64_e32 v[122:123], v[2:3]
	v_mov_b64_e32 v[124:125], v[2:3]
	v_mov_b64_e32 v[126:127], v[2:3]
	v_mov_b64_e32 v[128:129], v[2:3]
	v_readfirstlane_b32 s98, v219
	s_nop 1
	s_bitcmp1_b32 s98, 8
	s_cbranch_scc0 .Lresync_y_555
	s_barrier

; template <class Epi>
; __device__ __forceinline__ void gemm_phase(LAS unsigned char* lds, const Gemm g, const Sched& S, const Epi& E) {
;     ...
;         const bool has_next = S.next(ui + 1, nxt);
;         const char* nA = has_next ? (const char*)g.A + nxt.ao : cA; const char* nB = has_next ? (const char*)g.Bt + nxt.bo : cB;
;     ...
; #pragma unroll
;         for (int a = 0; a < 2; ++a)
; #pragma unroll
;             for (int b = 0; b < 2; ++b)
; #pragma unroll
;                 for (int m = 0; m < 4; ++m)
; #pragma unroll
;                     for (int n = 0; n < 2; ++n) acc[a][b][m][n] = (f32x4){0.f, 0.f, 0.f, 0.f};
;         cur = nxt; cA = nA; cB = nB; ++ui;
.LBB0_648:
	v_mov_b64_e32 v[2:3], s[26:27]
	v_readlane_b32 s8, v254, 11
	v_cmp_lt_i64_e32 vcc, s[82:83], v[2:3]
	v_readlane_b32 s9, v254, 12
	s_add_u32 s82, s8, s38
	s_addc_u32 s83, s9, s39
	s_and_b64 s[14:15], vcc, exec
	s_cselect_b32 s33, s83, s1
	s_cselect_b32 s48, s82, s0
	s_add_u32 s84, s10, s80
	s_addc_u32 s85, s11, s81
	s_and_b64 s[14:15], vcc, exec
	s_cselect_b32 s51, s85, s5
	s_cselect_b32 s55, s84, s4
	s_add_u32 s0, s0, 0x80
	s_addc_u32 s1, s1, 0
	s_add_u32 s34, s4, 0x100
	v_mov_b32_e32 v2, 0
	s_addc_u32 s35, s5, 0
	s_mov_b32 s4, 0
	s_waitcnt lgkmcnt(0)
	v_mov_b32_e32 v3, v2
	v_mov_b64_e32 v[4:5], v[2:3]
	v_mov_b64_e32 v[6:7], v[2:3]
	v_mov_b64_e32 v[8:9], v[2:3]
	v_mov_b64_e32 v[10:11], v[2:3]
	v_mov_b64_e32 v[12:13], v[2:3]
	v_mov_b64_e32 v[14:15], v[2:3]
	v_mov_b64_e32 v[16:17], v[2:3]
	v_mov_b64_e32 v[18:19], v[2:3]
	v_mov_b64_e32 v[20:21], v[2:3]
	v_mov_b64_e32 v[22:23], v[2:3]
	v_mov_b64_e32 v[24:25], v[2:3]
	v_mov_b64_e32 v[26:27], v[2:3]
	v_mov_b64_e32 v[28:29], v[2:3]
	v_mov_b64_e32 v[30:31], v[2:3]
	v_mov_b64_e32 v[32:33], v[2:3]
	v_mov_b64_e32 v[34:35], v[2:3]
	v_mov_b64_e32 v[36:37], v[2:3]
	v_mov_b64_e32 v[38:39], v[2:3]
	v_mov_b64_e32 v[40:41], v[2:3]
	v_mov_b64_e32 v[42:43], v[2:3]
	v_mov_b64_e32 v[44:45], v[2:3]
	v_mov_b64_e32 v[46:47], v[2:3]
	v_mov_b64_e32 v[48:49], v[2:3]
	v_mov_b64_e32 v[50:51], v[2:3]
	v_mov_b64_e32 v[52:53], v[2:3]
	v_mov_b64_e32 v[54:55], v[2:3]
	v_mov_b64_e32 v[56:57], v[2:3]
	v_mov_b64_e32 v[58:59], v[2:3]
	v_mov_b64_e32 v[60:61], v[2:3]
	v_mov_b64_e32 v[62:63], v[2:3]
	v_mov_b64_e32 v[64:65], v[2:3]
	v_mov_b64_e32 v[66:67], v[2:3]
	v_mov_b64_e32 v[68:69], v[2:3]
	v_mov_b64_e32 v[70:71], v[2:3]
	v_mov_b64_e32 v[72:73], v[2:3]
	v_mov_b64_e32 v[74:75], v[2:3]
	v_mov_b64_e32 v[76:77], v[2:3]
	v_mov_b64_e32 v[78:79], v[2:3]
	v_mov_b64_e32 v[80:81], v[2:3]
	v_mov_b64_e32 v[82:83], v[2:3]
	v_mov_b64_e32 v[84:85], v[2:3]
	v_mov_b64_e32 v[86:87], v[2:3]
	v_mov_b64_e32 v[88:89], v[2:3]
	v_mov_b64_e32 v[90:91], v[2:3]
	v_mov_b64_e32 v[92:93], v[2:3]
	v_mov_b64_e32 v[94:95], v[2:3]
	v_mov_b64_e32 v[96:97], v[2:3]
	v_mov_b64_e32 v[98:99], v[2:3]
	v_mov_b64_e32 v[100:101], v[2:3]
	v_mov_b64_e32 v[102:103], v[2:3]
	v_mov_b64_e32 v[104:105], v[2:3]
	v_mov_b64_e32 v[106:107], v[2:3]
	v_mov_b64_e32 v[108:109], v[2:3]
	v_mov_b64_e32 v[110:111], v[2:3]
	v_mov_b64_e32 v[112:113], v[2:3]
	v_mov_b64_e32 v[114:115], v[2:3]
	v_mov_b64_e32 v[116:117], v[2:3]
	v_mov_b64_e32 v[118:119], v[2:3]
	v_mov_b64_e32 v[120:121], v[2:3]
	v_mov_b64_e32 v[122:123], v[2:3]
	v_mov_b64_e32 v[124:125], v[2:3]
	v_mov_b64_e32 v[126:127], v[2:3]
	v_mov_b64_e32 v[128:129], v[2:3]
	v_readfirstlane_b32 s98, v219
	s_nop 1
	s_bitcmp1_b32 s98, 8
	s_cbranch_scc0 .Lresync_y_649
	s_barrier

; template <class Epi>
; __device__ __forceinline__ void gemm_phase(LAS unsigned char* lds, const Gemm g, const Sched& S, const Epi& E) {
;     ...
;         const bool has_next = S.next(ui + 1, nxt);
;         const char* nA = has_next ? (const char*)g.A + nxt.ao : cA; const char* nB = has_next ? (const char*)g.Bt + nxt.bo : cB;
;     ...
; #pragma unroll
;         for (int a = 0; a < 2; ++a)
; #pragma unroll
;             for (int b = 0; b < 2; ++b)
; #pragma unroll
;                 for (int m = 0; m < 4; ++m)
; #pragma unroll
;                     for (int n = 0; n < 2; ++n) acc[a][b][m][n] = (f32x4){0.f, 0.f, 0.f, 0.f};
;         cur = nxt; cA = nA; cB = nB; ++ui;
.LBB0_718:
	v_mov_b64_e32 v[2:3], s[26:27]
	v_readlane_b32 s8, v254, 11
	v_cmp_lt_i64_e32 vcc, s[90:91], v[2:3]
	v_readlane_b32 s9, v254, 12
	s_add_u32 s90, s8, s86
	s_addc_u32 s91, s9, s87
	s_and_b64 s[14:15], vcc, exec
	s_cselect_b32 s57, s91, s1
	s_cselect_b32 s59, s90, s0
	s_add_u32 s92, s10, s88
	s_addc_u32 s93, s11, s89
	s_and_b64 s[14:15], vcc, exec
	s_cselect_b32 vcc_lo, s93, s5
	s_cselect_b32 vcc_hi, s92, s4
	s_add_u32 s0, s0, 0x80
	s_addc_u32 s1, s1, 0
	s_add_u32 s34, s4, 0x100
	v_mov_b32_e32 v2, 0
	s_addc_u32 s35, s5, 0
	s_mov_b32 s4, 0
	v_mov_b32_e32 v3, v2
	v_mov_b64_e32 v[4:5], v[2:3]
	v_mov_b64_e32 v[6:7], v[2:3]
	v_mov_b64_e32 v[8:9], v[2:3]
	v_mov_b64_e32 v[10:11], v[2:3]
	v_mov_b64_e32 v[12:13], v[2:3]
	v_mov_b64_e32 v[14:15], v[2:3]
	v_mov_b64_e32 v[16:17], v[2:3]
	v_mov_b64_e32 v[18:19], v[2:3]
	v_mov_b64_e32 v[20:21], v[2:3]
	v_mov_b64_e32 v[22:23], v[2:3]
	v_mov_b64_e32 v[24:25], v[2:3]
	v_mov_b64_e32 v[26:27], v[2:3]
	v_mov_b64_e32 v[28:29], v[2:3]
	v_mov_b64_e32 v[30:31], v[2:3]
	v_mov_b64_e32 v[32:33], v[2:3]
	v_mov_b64_e32 v[34:35], v[2:3]
	v_mov_b64_e32 v[36:37], v[2:3]
	v_mov_b64_e32 v[38:39], v[2:3]
	v_mov_b64_e32 v[40:41], v[2:3]
	v_mov_b64_e32 v[42:43], v[2:3]
	v_mov_b64_e32 v[44:45], v[2:3]
	v_mov_b64_e32 v[46:47], v[2:3]
	v_mov_b64_e32 v[48:49], v[2:3]
	v_mov_b64_e32 v[50:51], v[2:3]
	v_mov_b64_e32 v[52:53], v[2:3]
	v_mov_b64_e32 v[54:55], v[2:3]
	v_mov_b64_e32 v[56:57], v[2:3]
	v_mov_b64_e32 v[58:59], v[2:3]
	v_mov_b64_e32 v[60:61], v[2:3]
	v_mov_b64_e32 v[62:63], v[2:3]
	v_mov_b64_e32 v[64:65], v[2:3]
	v_mov_b64_e32 v[66:67], v[2:3]
	v_mov_b64_e32 v[68:69], v[2:3]
	v_mov_b64_e32 v[70:71], v[2:3]
	v_mov_b64_e32 v[72:73], v[2:3]
	v_mov_b64_e32 v[74:75], v[2:3]
	v_mov_b64_e32 v[76:77], v[2:3]
	v_mov_b64_e32 v[78:79], v[2:3]
	v_mov_b64_e32 v[80:81], v[2:3]
	v_mov_b64_e32 v[82:83], v[2:3]
	v_mov_b64_e32 v[84:85], v[2:3]
	v_mov_b64_e32 v[86:87], v[2:3]
	v_mov_b64_e32 v[88:89], v[2:3]
	v_mov_b64_e32 v[90:91], v[2:3]
	v_mov_b64_e32 v[92:93], v[2:3]
	v_mov_b64_e32 v[94:95], v[2:3]
	v_mov_b64_e32 v[96:97], v[2:3]
	v_mov_b64_e32 v[98:99], v[2:3]
	v_mov_b64_e32 v[100:101], v[2:3]
	v_mov_b64_e32 v[102:103], v[2:3]
	v_mov_b64_e32 v[104:105], v[2:3]
	v_mov_b64_e32 v[162:163], v[2:3]
	v_mov_b64_e32 v[164:165], v[2:3]
	v_mov_b64_e32 v[174:175], v[2:3]
	v_mov_b64_e32 v[176:177], v[2:3]
	v_mov_b64_e32 v[178:179], v[2:3]
	v_mov_b64_e32 v[180:181], v[2:3]
	v_mov_b64_e32 v[182:183], v[2:3]
	v_mov_b64_e32 v[184:185], v[2:3]
	v_mov_b64_e32 v[186:187], v[2:3]
	v_mov_b64_e32 v[188:189], v[2:3]
	v_mov_b64_e32 v[190:191], v[2:3]
	v_mov_b64_e32 v[192:193], v[2:3]
	v_readfirstlane_b32 s98, v219
	s_nop 1
	s_bitcmp1_b32 s98, 8
	s_cbranch_scc0 .Lresync_y_719
	s_barrier

; template <class Epi>
; __device__ __forceinline__ void gemm_phase(LAS unsigned char* lds, const Gemm g, const Sched& S, const Epi& E) {
;     ...
;         const bool has_next = S.next(ui + 1, nxt);
;         const char* nA = has_next ? (const char*)g.A + nxt.ao : cA; const char* nB = has_next ? (const char*)g.Bt + nxt.bo : cB;
;     ...
; #pragma unroll
;         for (int a = 0; a < 2; ++a)
; #pragma unroll
;             for (int b = 0; b < 2; ++b)
; #pragma unroll
;                 for (int m = 0; m < 4; ++m)
; #pragma unroll
;                     for (int n = 0; n < 2; ++n) acc[a][b][m][n] = (f32x4){0.f, 0.f, 0.f, 0.f};
;         cur = nxt; cA = nA; cB = nB; ++ui;
.LBB0_824:
	v_mov_b64_e32 v[2:3], s[26:27]
	v_cmp_lt_i64_e32 vcc, s[64:65], v[2:3]
	v_readlane_b32 s64, v254, 11
	v_readlane_b32 s65, v254, 12
	s_add_u32 s64, s64, s38
	s_addc_u32 s65, s65, s39
	s_and_b64 s[66:67], vcc, exec
	s_cselect_b32 s57, s65, s5
	s_cselect_b32 s59, s64, s4
	s_add_u32 s66, s10, s40
	s_addc_u32 s67, s11, s41
	s_and_b64 s[70:71], vcc, exec
	s_cselect_b32 s82, s67, s69
	s_cselect_b32 s83, s66, s68
	s_add_u32 s4, s4, 0x80
	s_addc_u32 s5, s5, 0
	s_add_u32 s84, s68, 0x100
	v_mov_b32_e32 v2, 0
	s_addc_u32 s85, s69, 0
	s_mov_b32 s68, 0
	v_mov_b32_e32 v3, v2
	v_mov_b64_e32 v[4:5], v[2:3]
	v_mov_b64_e32 v[6:7], v[2:3]
	v_mov_b64_e32 v[8:9], v[2:3]
	v_mov_b64_e32 v[10:11], v[2:3]
	v_mov_b64_e32 v[12:13], v[2:3]
	v_mov_b64_e32 v[14:15], v[2:3]
	v_mov_b64_e32 v[16:17], v[2:3]
	v_mov_b64_e32 v[18:19], v[2:3]
	v_mov_b64_e32 v[20:21], v[2:3]
	v_mov_b64_e32 v[22:23], v[2:3]
	v_mov_b64_e32 v[24:25], v[2:3]
	v_mov_b64_e32 v[26:27], v[2:3]
	v_mov_b64_e32 v[28:29], v[2:3]
	v_mov_b64_e32 v[30:31], v[2:3]
	v_mov_b64_e32 v[32:33], v[2:3]
	v_mov_b64_e32 v[34:35], v[2:3]
	v_mov_b64_e32 v[36:37], v[2:3]
	v_mov_b64_e32 v[38:39], v[2:3]
	v_mov_b64_e32 v[40:41], v[2:3]
	v_mov_b64_e32 v[42:43], v[2:3]
	v_mov_b64_e32 v[44:45], v[2:3]
	v_mov_b64_e32 v[46:47], v[2:3]
	v_mov_b64_e32 v[48:49], v[2:3]
	v_mov_b64_e32 v[50:51], v[2:3]
	v_mov_b64_e32 v[52:53], v[2:3]
	v_mov_b64_e32 v[54:55], v[2:3]
	v_mov_b64_e32 v[56:57], v[2:3]
	v_mov_b64_e32 v[58:59], v[2:3]
	v_mov_b64_e32 v[60:61], v[2:3]
	v_mov_b64_e32 v[62:63], v[2:3]
	v_mov_b64_e32 v[64:65], v[2:3]
	v_mov_b64_e32 v[66:67], v[2:3]
	v_mov_b64_e32 v[68:69], v[2:3]
	v_mov_b64_e32 v[70:71], v[2:3]
	v_mov_b64_e32 v[72:73], v[2:3]
	v_mov_b64_e32 v[74:75], v[2:3]
	v_mov_b64_e32 v[76:77], v[2:3]
	v_mov_b64_e32 v[78:79], v[2:3]
	v_mov_b64_e32 v[80:81], v[2:3]
	v_mov_b64_e32 v[82:83], v[2:3]
	v_mov_b64_e32 v[84:85], v[2:3]
	v_mov_b64_e32 v[86:87], v[2:3]
	v_mov_b64_e32 v[88:89], v[2:3]
	v_mov_b64_e32 v[90:91], v[2:3]
	v_mov_b64_e32 v[92:93], v[2:3]
	v_mov_b64_e32 v[94:95], v[2:3]
	v_mov_b64_e32 v[96:97], v[2:3]
	v_mov_b64_e32 v[98:99], v[2:3]
	v_mov_b64_e32 v[100:101], v[2:3]
	v_mov_b64_e32 v[102:103], v[2:3]
	v_mov_b64_e32 v[104:105], v[2:3]
	v_mov_b64_e32 v[106:107], v[2:3]
	v_mov_b64_e32 v[108:109], v[2:3]
	v_mov_b64_e32 v[110:111], v[2:3]
	v_mov_b64_e32 v[112:113], v[2:3]
	v_mov_b64_e32 v[114:115], v[2:3]
	v_mov_b64_e32 v[116:117], v[2:3]
	v_mov_b64_e32 v[118:119], v[2:3]
	v_mov_b64_e32 v[120:121], v[2:3]
	v_mov_b64_e32 v[122:123], v[2:3]
	v_mov_b64_e32 v[124:125], v[2:3]
	v_mov_b64_e32 v[126:127], v[2:3]
	v_mov_b64_e32 v[128:129], v[2:3]
	v_readfirstlane_b32 s98, v219
	s_nop 1
	s_bitcmp1_b32 s98, 8
	s_cbranch_scc0 .Lresync_y_825
	s_barrier
